# v26 plus loop-exit test (and ring toggles) rotated in front of the loop-back barrier in both attention loops, exit path gets its own barrier copy
# speedup vs baseline: 1.0086x; 1.0086x over previous
; #define SWRITE(b, i) do { *(bf16x8*)(V_lds + (b) * SHM_V + vst0) = st_[i].vs; *(bf16x8*)(K_lds + (b) * SHM_K + kst0) = st_[i].ks; \
;     if (DQ == 96) { if (tid < 256) *(bf16x8*)(K_lds + (b) * SHM_K + kst2) = st_[i].kr; } } while (0)
; #define SWAIT() do { if (DQ == 96) asm volatile("s_waitcnt vmcnt(3)" ::: "memory"); else asm volatile("s_waitcnt vmcnt(2)" ::: "memory"); } while (0)
; #define SWRITE(b, i) do { *(bf16x8*)(V_lds + (b) * SHM_V + vst0) = st_[i].vs; *(bf16x8*)(K_lds + (b) * SHM_K + kst0) = st_[i].ks; \
;     if (DQ == 96) { if (tid < 256) *(bf16x8*)(K_lds + (b) * SHM_K + kst2) = st_[i].kr; } } while (0)
; #define SWAIT() do { if (DQ == 96) asm volatile("s_waitcnt vmcnt(3)" ::: "memory"); else asm volatile("s_waitcnt vmcnt(2)" ::: "memory"); } while (0)
; template <int DQ, bool WIN, int LDQ, int LDK> ...
;     ...
;         pv(vb0 + SHM_V);
;         __syncthreads(); SWAIT(); SWRITE(1, SO);
;         lsum_upd();
;         if (WIN) win_mask(pA0, pA1, qrow - KBASE(j + 1), hi);
;         exp16(pA0);
;         __syncthreads();
.LBB0_492:
	ds_read_b64_tr_b16 v[168:169], v155 offset:0x1000
	ds_read_b64_tr_b16 v[170:171], v155 offset:0x1400
	ds_read_b64_tr_b16 v[172:173], v155 offset:0x1800
	ds_read_b64_tr_b16 v[174:175], v155 offset:0x1c00
	ds_read_b64_tr_b16 v[160:161], v155 offset:0x200
	ds_read_b64_tr_b16 v[162:163], v155 offset:0x600
	ds_read_b64_tr_b16 v[164:165], v155 offset:0xa00
	ds_read_b64_tr_b16 v[166:167], v155 offset:0xe00
	v_mfma_f32_32x32x16_bf16 v[2:17], v[94:97], v[42:45], v[2:17]
	v_mfma_f32_32x32x16_bf16 v[2:17], v[90:93], v[46:49], v[2:17]
	s_waitcnt lgkmcnt(6)
	v_mfma_f32_32x32x16_bf16 v[2:17], v[86:89], v[168:171], v[2:17]
	ds_read_b64_tr_b16 v[168:169], v155 offset:0x1200
	ds_read_b64_tr_b16 v[170:171], v155 offset:0x1600
	s_waitcnt lgkmcnt(6)
	v_mfma_f32_32x32x16_bf16 v[2:17], v[82:85], v[172:175], v[2:17]
	ds_read_b64_tr_b16 v[176:177], v155 offset:0x1a00
	ds_read_b64_tr_b16 v[178:179], v155 offset:0x1e00
	s_waitcnt lgkmcnt(0)
	v_mfma_f32_32x32x16_bf16 v[18:33], v[94:97], v[160:163], v[18:33]
	s_waitcnt vmcnt(2)
	ds_write_b128 v158, v[138:141] offset:8192
	ds_write_b128 v157, v[142:145] offset:25600
	v_exp_f32_e32 v138, v98
	v_exp_f32_e32 v139, v99
	v_mfma_f32_32x32x16_bf16 v[18:33], v[90:93], v[164:167], v[18:33]
	v_exp_f32_e32 v162, v100
	v_exp_f32_e32 v165, v101
	v_exp_f32_e32 v163, v102
	v_exp_f32_e32 v166, v103
	v_exp_f32_e32 v164, v104
	v_exp_f32_e32 v167, v105
	v_exp_f32_e32 v140, v106
	v_mfma_f32_32x32x16_bf16 v[18:33], v[86:89], v[168:171], v[18:33]
	v_exp_f32_e32 v144, v107
	v_exp_f32_e32 v141, v108
	v_exp_f32_e32 v145, v109
	v_exp_f32_e32 v142, v110
	v_exp_f32_e32 v160, v111
	v_mfma_f32_16x16x32_bf16 v[34:37], v[94:97], v[38:41], v[34:37]
	v_exp_f32_e32 v143, v112
	v_exp_f32_e32 v161, v113
	v_lshl_add_u64 v[148:149], v[148:149], 0, s[18:19]
	v_xor_b32_e32 v158, 0xc000, v158
	v_xor_b32_e32 v159, 0xc000, v159
	v_xor_b32_e32 v155, 0xc000, v155
	s_cmpk_gt_u32 s21, 0x7c
	s_cbranch_scc1 .Ldense_exit
	s_waitcnt lgkmcnt(0)
	s_barrier
	v_mfma_f32_16x16x32_bf16 v[34:37], v[90:93], v[38:41], v[34:37]
	v_mfma_f32_16x16x32_bf16 v[34:37], v[86:89], v[38:41], v[34:37]
	v_mfma_f32_32x32x16_bf16 v[18:33], v[82:85], v[176:179], v[18:33]
	v_mfma_f32_16x16x32_bf16 v[34:37], v[82:85], v[38:41], v[34:37]

; #define SWRITE(b, i) do { *(bf16x8*)(V_lds + (b) * SHM_V + vst0) = st_[i].vs; *(bf16x8*)(K_lds + (b) * SHM_K + kst0) = st_[i].ks; \
;     if (DQ == 96) { if (tid < 256) *(bf16x8*)(K_lds + (b) * SHM_K + kst2) = st_[i].kr; } } while (0)
; #define SWAIT() do { if (DQ == 96) asm volatile("s_waitcnt vmcnt(3)" ::: "memory"); else asm volatile("s_waitcnt vmcnt(2)" ::: "memory"); } while (0)
; #define SWRITE(b, i) do { *(bf16x8*)(V_lds + (b) * SHM_V + vst0) = st_[i].vs; *(bf16x8*)(K_lds + (b) * SHM_K + kst0) = st_[i].ks; \
;     if (DQ == 96) { if (tid < 256) *(bf16x8*)(K_lds + (b) * SHM_K + kst2) = st_[i].kr; } } while (0)
; #define SWAIT() do { if (DQ == 96) asm volatile("s_waitcnt vmcnt(3)" ::: "memory"); else asm volatile("s_waitcnt vmcnt(2)" ::: "memory"); } while (0)
; template <int DQ, bool WIN, int LDQ, int LDK> ...
;     ...
;         pv(vb0 + SHM_V);
;         __syncthreads(); SWAIT(); SWRITE(1, SO);
;         lsum_upd();
;         if (WIN) win_mask(pA0, pA1, qrow - KBASE(j + 1), hi);
;         exp16(pA0);
;         __syncthreads();
.Ldense_exit:
	s_waitcnt lgkmcnt(0)
	s_barrier
	v_mfma_f32_16x16x32_bf16 v[34:37], v[90:93], v[38:41], v[34:37]
	v_mfma_f32_16x16x32_bf16 v[34:37], v[86:89], v[38:41], v[34:37]
	v_mfma_f32_32x32x16_bf16 v[18:33], v[82:85], v[176:179], v[18:33]
	v_mfma_f32_16x16x32_bf16 v[34:37], v[82:85], v[38:41], v[34:37]

; #define SBAR() __builtin_amdgcn_sched_barrier(0)
; #define SLOAD(i, k0) do { st_[i].vs = *reinterpret_cast<const bf16x8*>(&Vh[(size_t)((k0) + sr) * LDK + sc]); \
;     st_[i].ks = *reinterpret_cast<const bf16x8*>(&Kh[(size_t)((k0) + sr) * LDK + sc]); \
;     if (DQ == 96) st_[i].kr = *reinterpret_cast<const bf16x8*>(&Kr[(size_t)((k0) + sr2) * 32 + sc2]); } while (0)
; #define SWRITE(b, i) do { *(bf16x8*)(V_lds + (b) * SHM_V + vst0) = st_[i].vs; *(bf16x8*)(K_lds + (b) * SHM_K + kst0) = st_[i].ks; \
;     if (DQ == 96) { if (tid < 256) *(bf16x8*)(K_lds + (b) * SHM_K + kst2) = st_[i].kr; } } while (0)
; #define SWAIT() do { if (DQ == 96) asm volatile("s_waitcnt vmcnt(3)" ::: "memory"); else asm volatile("s_waitcnt vmcnt(2)" ::: "memory"); } while (0)
; #define SLOAD(i, k0) do { st_[i].vs = *reinterpret_cast<const bf16x8*>(&Vh[(size_t)((k0) + sr) * LDK + sc]); \
;     st_[i].ks = *reinterpret_cast<const bf16x8*>(&Kh[(size_t)((k0) + sr) * LDK + sc]); \
;     if (DQ == 96) st_[i].kr = *reinterpret_cast<const bf16x8*>(&Kr[(size_t)((k0) + sr2) * 32 + sc2]); } while (0)
; #define SWRITE(b, i) do { *(bf16x8*)(V_lds + (b) * SHM_V + vst0) = st_[i].vs; *(bf16x8*)(K_lds + (b) * SHM_K + kst0) = st_[i].ks; \
;     if (DQ == 96) { if (tid < 256) *(bf16x8*)(K_lds + (b) * SHM_K + kst2) = st_[i].kr; } } while (0)
; #define SWAIT() do { if (DQ == 96) asm volatile("s_waitcnt vmcnt(3)" ::: "memory"); else asm volatile("s_waitcnt vmcnt(2)" ::: "memory"); } while (0)
; template <int DQ, bool WIN, int LDQ, int LDK> ...
;     ...
;         exp16(pB0);
;         __syncthreads();
;         SBAR(); qkt<DQ>(pA0, pA1, K_lds, qr, minit, r32, hi);
;         finish(pB0, pB1); SBAR();
;         if (j + 3 < NT) SLOAD(SE, KBASE(j + 3)); SBAR();
;         pv(vb0 + SHM_V);
;         __syncthreads(); SWAIT(); SWRITE(1, SO);
;         lsum_upd();
;         if (WIN) win_mask(pA0, pA1, qrow - KBASE(j + 1), hi);
;         exp16(pA0);
;         __syncthreads();
.LBB0_1093:
	v_xor_b32_e32 v192, 0xc000, v192
	v_xor_b32_e32 v194, 0xc000, v194
	v_xor_b32_e32 v190, 0xc000, v190
	v_exp_f32_e32 v161, v96
	v_exp_f32_e32 v196, v97
	v_mfma_f32_16x16x32_bf16 v[32:35], v[80:83], v[36:39], v[32:35]
	v_exp_f32_e32 v158, v98
	v_exp_f32_e32 v168, v99
	v_exp_f32_e32 v159, v100
	v_exp_f32_e32 v169, v101
	v_exp_f32_e32 v160, v102
	v_exp_f32_e32 v195, v103
	v_exp_f32_e32 v154, v105
	v_mfma_f32_16x16x32_bf16 v[32:35], v[84:87], v[36:39], v[32:35]
	v_exp_f32_e32 v155, v107
	v_exp_f32_e32 v156, v109
	v_exp_f32_e32 v157, v111
	v_lshl_add_u64 v[162:163], v[162:163], 0, s[34:35]
	v_lshl_add_u64 v[164:165], v[164:165], 0, s[18:19]
	v_mfma_f32_16x16x32_bf16 v[32:35], v[88:91], v[36:39], v[32:35]
	v_lshl_add_u64 v[166:167], v[166:167], 0, s[34:35]
	s_cmpk_gt_u32 s17, 0x7c
	s_cbranch_scc1 .Lmla_exit
	s_waitcnt lgkmcnt(0)
	s_barrier
	v_mfma_f32_16x16x32_bf16 v[32:35], v[92:95], v[36:39], v[32:35]
	v_exp_f32_e32 v150, v104
	v_exp_f32_e32 v151, v106
	v_exp_f32_e32 v152, v108
	v_exp_f32_e32 v153, v110

; #define SWRITE(b, i) do { *(bf16x8*)(V_lds + (b) * SHM_V + vst0) = st_[i].vs; *(bf16x8*)(K_lds + (b) * SHM_K + kst0) = st_[i].ks; \
;     if (DQ == 96) { if (tid < 256) *(bf16x8*)(K_lds + (b) * SHM_K + kst2) = st_[i].kr; } } while (0)
; #define SWAIT() do { if (DQ == 96) asm volatile("s_waitcnt vmcnt(3)" ::: "memory"); else asm volatile("s_waitcnt vmcnt(2)" ::: "memory"); } while (0)
; #define SWRITE(b, i) do { *(bf16x8*)(V_lds + (b) * SHM_V + vst0) = st_[i].vs; *(bf16x8*)(K_lds + (b) * SHM_K + kst0) = st_[i].ks; \
;     if (DQ == 96) { if (tid < 256) *(bf16x8*)(K_lds + (b) * SHM_K + kst2) = st_[i].kr; } } while (0)
; #define SWAIT() do { if (DQ == 96) asm volatile("s_waitcnt vmcnt(3)" ::: "memory"); else asm volatile("s_waitcnt vmcnt(2)" ::: "memory"); } while (0)
; template <int DQ, bool WIN, int LDQ, int LDK> ...
;     ...
;         pv(vb0 + SHM_V);
;         __syncthreads(); SWAIT(); SWRITE(1, SO);
;         lsum_upd();
;         if (WIN) win_mask(pA0, pA1, qrow - KBASE(j + 1), hi);
;         exp16(pA0);
;         __syncthreads();
.Lmla_exit:
	s_waitcnt lgkmcnt(0)
	s_barrier
	v_mfma_f32_16x16x32_bf16 v[32:35], v[92:95], v[36:39], v[32:35]
	v_exp_f32_e32 v150, v104
	v_exp_f32_e32 v151, v106
	v_exp_f32_e32 v152, v108
	v_exp_f32_e32 v153, v110
